# GLA weight staging loads hoisted in prep (8 loads in flight); init unroll x2
# speedup vs baseline: 1.0045x; 1.0045x over previous
; __device__ __forceinline__ unsigned f2bf(float f) { return pk2(f, 0.f) & 0xffffu; }
; __device__ __forceinline__ void phase_prep(const Frame& F, ArgsRef A, int l) {
;     ...
;         for (int e = F.tid; e < 2 * 16 * 1024; e += NTHR) { const int dr = e >> 10, cc = e & 1023, dir = dr >> 4, r = dr & 15; TW[(dir * 1024 + cc) * 16 + r] = (unsigned short)f2bf(wa2[e]); }
.LBB0_582:
	v_ashrrev_i32_e32 v13, 31, v7
	v_mov_b32_e32 v12, v7
	v_ashrrev_i32_e32 v15, 31, v6
	v_mov_b32_e32 v14, v6
	v_lshl_add_u64 v[14:15], v[14:15], 2, s[12:13]
	v_lshl_add_u64 v[12:13], v[12:13], 2, s[12:13]
	v_add_co_u32_e32 v70, vcc, 0x1000, v14
	s_nop 1
	v_addc_co_u32_e32 v71, vcc, 0, v15, vcc
	v_add_co_u32_e32 v76, vcc, 0x1000, v12
	s_nop 1
	v_addc_co_u32_e32 v77, vcc, 0, v13, vcc
	v_add_co_u32_e32 v72, vcc, 0x2000, v14
	s_nop 1
	v_addc_co_u32_e32 v73, vcc, 0, v15, vcc
	v_add_co_u32_e32 v78, vcc, 0x2000, v12
	s_nop 1
	v_addc_co_u32_e32 v79, vcc, 0, v13, vcc
	v_add_co_u32_e32 v74, vcc, 0x3000, v14
	s_nop 1
	v_addc_co_u32_e32 v75, vcc, 0, v15, vcc
	v_add_co_u32_e32 v80, vcc, 0x3000, v12
	s_nop 1
	v_addc_co_u32_e32 v81, vcc, 0, v13, vcc
	global_load_dword v14, v[14:15], off
	s_nop 0
	global_load_dword v12, v[12:13], off
	global_load_dword v82, v[70:71], off
	global_load_dword v83, v[76:77], off
	global_load_dword v84, v[72:73], off
	global_load_dword v85, v[78:79], off
	global_load_dword v86, v[74:75], off
	global_load_dword v87, v[80:81], off
	v_lshrrev_b32_e32 v11, 10, v6
	v_lshrrev_b32_e32 v5, 10, v7
	v_and_b32_e32 v11, 15, v11
	v_lshlrev_b32_e32 v13, 4, v7
	v_and_b32_e32 v16, 0xffffc000, v6
	v_and_b32_e32 v5, 15, v5
	v_and_b32_e32 v13, 0x3ff0, v13
	v_and_b32_e32 v15, 0xffffc000, v7
	v_lshl_add_u32 v16, v16, 1, 0
	v_lshlrev_b32_e32 v11, 1, v11
	v_lshl_add_u32 v15, v15, 1, 0
	v_lshlrev_b32_e32 v21, 1, v13
	v_lshlrev_b32_e32 v5, 1, v5
	v_add3_u32 v5, v15, v21, v5
	v_add_u32_e32 v10, -4, v10
	v_cmp_eq_u32_e32 vcc, 0, v10
	s_or_b64 s[22:23], vcc, s[22:23]
	s_waitcnt vmcnt(6)
	v_cvt_pk_bf16_f32 v12, v14, v12
	v_lshlrev_b32_e32 v14, 4, v6
	v_and_b32_e32 v14, 0x3ff0, v14
	v_lshlrev_b32_e32 v20, 1, v14
	v_add3_u32 v11, v16, v20, v11
	v_add_u32_e32 v14, 0x400, v6
	ds_write_b16 v11, v12
	ds_write_b16_d16_hi v5, v12
	v_add_u32_e32 v12, 0x400, v7
	v_ashrrev_i32_e32 v15, 31, v14
	v_ashrrev_i32_e32 v13, 31, v12
	v_lshl_add_u64 v[16:17], v[14:15], 2, s[12:13]
	v_lshl_add_u64 v[18:19], v[12:13], 2, s[12:13]
	s_nop 0
	s_nop 0
	v_lshrrev_b32_e32 v11, 10, v14
	v_lshrrev_b32_e32 v5, 10, v12
	v_and_b32_e32 v11, 15, v11
	v_and_b32_e32 v14, 0xffffc000, v14
	v_and_b32_e32 v5, 15, v5
	v_and_b32_e32 v12, 0xffffc000, v12
	v_lshl_add_u32 v14, v14, 1, 0
	v_lshlrev_b32_e32 v11, 1, v11
	v_lshl_add_u32 v12, v12, 1, 0
	v_add3_u32 v11, v14, v20, v11
	v_lshlrev_b32_e32 v5, 1, v5
	v_add_u32_e32 v14, 0x800, v6
	v_add3_u32 v5, v12, v21, v5
	v_add_u32_e32 v12, 0x800, v7
	s_waitcnt vmcnt(4)
	v_cvt_pk_bf16_f32 v13, v82, v83
	v_ashrrev_i32_e32 v15, 31, v14
	ds_write_b16 v11, v13
	ds_write_b16_d16_hi v5, v13
	v_ashrrev_i32_e32 v13, 31, v12
	v_lshl_add_u64 v[16:17], v[14:15], 2, s[12:13]
	v_lshl_add_u64 v[18:19], v[12:13], 2, s[12:13]
	s_nop 0
	s_nop 0
	v_lshrrev_b32_e32 v11, 10, v14
	v_lshrrev_b32_e32 v5, 10, v12
	v_and_b32_e32 v11, 15, v11
	v_and_b32_e32 v14, 0xffffc000, v14
	v_and_b32_e32 v5, 15, v5
	v_and_b32_e32 v12, 0xffffc000, v12
	v_lshl_add_u32 v14, v14, 1, 0
	v_lshlrev_b32_e32 v11, 1, v11
	v_lshl_add_u32 v12, v12, 1, 0
	v_add3_u32 v11, v14, v20, v11
	v_lshlrev_b32_e32 v5, 1, v5
	v_add_u32_e32 v14, 0xc00, v6
	v_add3_u32 v5, v12, v21, v5
	v_add_u32_e32 v12, 0xc00, v7
	v_add_u32_e32 v7, 0x1000, v7
	v_add_u32_e32 v6, 0x1000, v6
	s_waitcnt vmcnt(2)
	v_cvt_pk_bf16_f32 v13, v84, v85
	v_ashrrev_i32_e32 v15, 31, v14
	ds_write_b16 v11, v13
	ds_write_b16_d16_hi v5, v13
	v_ashrrev_i32_e32 v13, 31, v12
	v_lshl_add_u64 v[16:17], v[14:15], 2, s[12:13]
	v_lshl_add_u64 v[18:19], v[12:13], 2, s[12:13]
	s_nop 0
	s_nop 0
	v_lshrrev_b32_e32 v11, 10, v14
	v_lshrrev_b32_e32 v5, 10, v12
	v_and_b32_e32 v11, 15, v11
	v_and_b32_e32 v14, 0xffffc000, v14
	v_and_b32_e32 v5, 15, v5
	v_and_b32_e32 v12, 0xffffc000, v12
	v_lshl_add_u32 v14, v14, 1, 0
	v_lshlrev_b32_e32 v11, 1, v11
	v_lshl_add_u32 v12, v12, 1, 0
	v_add3_u32 v11, v14, v20, v11
	v_lshlrev_b32_e32 v5, 1, v5
	v_add3_u32 v5, v12, v21, v5
	s_waitcnt vmcnt(0)
	v_cvt_pk_bf16_f32 v13, v86, v87
	ds_write_b16 v11, v13
	ds_write_b16_d16_hi v5, v13
	s_andn2_b64 exec, exec, s[22:23]
	s_cbranch_execnz .LBB0_582
	s_or_b64 exec, exec, s[22:23]
